# PRO weight-transpose loop rotated: next tile's loads issued right after this tile's LDS writes, descriptor chain for the tile after moved to the end of the iteration (in the loads' shadow)
# baseline (speedup 1.0000x reference)
.Lpro_dtest:
	s_cmpk_gt_i32 s20, 0x28ff
	s_cbranch_scc0 .Lpro_desc

.Lpro_nogain:
	ds_write2_b32 v21, v2, v3 offset1:1
	ds_write2_b32 v21, v4, v5 offset0:2 offset1:3
	ds_write2_b32 v17, v6, v7 offset1:1
	v_add_u32_e32 v17, 0x2088, v21
	ds_write2_b32 v17, v8, v9 offset1:1
	s_waitcnt lgkmcnt(0)
	s_cmpk_gt_i32 s20, 0x28ff
	s_cbranch_scc0 .LBB0_641
.Lpro_bar:
	s_barrier
	s_branch .LBB0_624
.Lpro_desc:
	s_cmpk_gt_i32 s20, 0x15ff
	s_mov_b64 s[42:43], -1
	s_cbranch_scc0 .LBB0_639
	s_cmpk_gt_u32 s20, 0x20ff
	s_cbranch_scc0 .LBB0_636
	s_cmpk_gt_u32 s20, 0x26ff
	s_mov_b64 s[38:39], -1
	s_cbranch_scc0 .LBB0_630
	s_add_i32 s30, s20, 0xffffd900
	s_lshr_b32 s30, s30, 8
	s_mov_b32 s31, s80
	s_lshl_b64 s[36:37], s[30:31], 22
	s_add_u32 s36, s64, s36
	s_addc_u32 s37, s65, s37
	s_and_b32 s38, s21, 0x3c0
	s_lshl_b32 s39, s38, 12
	s_add_u32 s36, s36, s39
	s_addc_u32 s37, s37, 0
	s_and_b32 s39, s23, 0x3c0
	s_lshl_b32 s40, s39, 2
	s_add_u32 s36, s36, s40
	s_addc_u32 s37, s37, 0
	s_lshl_b64 s[30:31], s[30:31], 21
	s_add_u32 s30, s15, s30
	s_addc_u32 s31, s16, s31
	s_lshl_b32 s39, s39, 11
	s_add_u32 s30, s30, s39
	s_addc_u32 s31, s31, 0
	s_lshl_b32 s38, s38, 1
	s_add_u32 s30, s30, s38
	s_addc_u32 s31, s31, 0
	s_mov_b64 s[38:39], 0

.LBB0_639:
	s_andn2_b64 vcc, exec, s[42:43]
	s_cbranch_vccnz .LBB0_625
	s_mul_hi_i32 s30, s20, 0x2e8ba2e9
	s_lshr_b32 s31, s30, 31
	s_ashr_i32 s30, s30, 8
	s_add_i32 s31, s30, s31
	s_mul_i32 s30, s31, 0xfffffa80
	s_add_i32 s30, s20, s30
	s_mul_i32 s36, s30, 0xba3
	s_lshr_b32 s37, s36, 31
	s_ashr_i32 s36, s36, 18
	s_add_i32 s36, s36, s37
	s_mul_i32 s37, s36, 0x58
	s_sub_i32 s37, s30, s37
	s_sext_i32_i16 s38, s37
	s_lshl_b32 s30, s38, 6
	s_mul_i32 s40, s31, 0x1600000
	s_sext_i32_i16 s36, s36
	s_mul_hi_i32 s39, s31, 0x1600000
	s_add_u32 s42, s66, s40
	s_addc_u32 s39, s67, s39
	s_lshl_b32 s40, s36, 6
	s_ashr_i32 s41, s40, 31
	s_mul_i32 s36, s36, 0x160000
	s_mul_hi_i32 s43, s40, 0x5800
	s_add_u32 s36, s42, s36
	s_addc_u32 s39, s39, s43
	s_bitcmp0_b32 s37, 1
	s_cselect_b32 s37, 0, 0x2c00
	s_add_u32 s42, s36, s37
	s_addc_u32 s39, s39, 0
	s_lshl_b32 s36, s38, 5
	s_and_b32 s36, s36, 0xffffff80
	s_ashr_i32 s37, s36, 31
	s_lshl_b64 s[36:37], s[36:37], 2
	s_add_u32 s36, s42, s36
	s_addc_u32 s37, s39, s37
	s_lshl_b32 s38, s38, 8
	s_and_b32 s38, s38, 0x100
	s_add_u32 s36, s36, s38
	s_addc_u32 s37, s37, 0
	s_lshl_b32 s38, s31, 12
	s_ashr_i32 s39, s38, 31
	s_lshl_b64 s[38:39], s[38:39], 2
	s_add_u32 s42, s76, s38
	s_addc_u32 s43, s77, s39
	s_lshl_b64 s[38:39], s[40:41], 2
	s_add_u32 s38, s42, s38
	s_addc_u32 s39, s43, s39
	s_add_u32 s38, s38, 0x2000
	s_addc_u32 s39, s39, 0
	s_mul_hi_i32 s42, s31, 0xb00000
	s_mul_i32 s31, s31, 0xb00000
	s_add_u32 s43, s18, s31
	s_addc_u32 s42, s19, s42
	s_ashr_i32 s31, s30, 31
	s_lshl_b64 s[30:31], s[30:31], 11
	s_add_u32 s43, s43, s30
	s_addc_u32 s42, s42, s31
	s_lshl_b64 s[30:31], s[40:41], 1
	s_add_u32 s30, s43, s30
	s_addc_u32 s31, s42, s31
	s_movk_i32 s45, 0x400
	s_mov_b64 s[40:41], 0x1600
	s_branch .LBB0_625
